# mLSTM scan: precomputed per-lane offsets + scalar bases for prefetch loads, q/k loads spread over compute, x-conv batched loads, LN-epilogue L1 invalidate dropped
# speedup vs baseline: 1.0030x; 1.0030x over previous
.LBB0_17:
	v_add_co_u32_e32 v10, vcc, 0xfffff000, v4
	s_add_i32 s10, s10, s84
	s_nop 0
	v_addc_co_u32_e32 v11, vcc, -1, v5, vcc
	global_load_dwordx4 v[12:15], v[10:11], off offset:-3072 nt
	global_load_dwordx4 v[16:19], v[10:11], off offset:-2048 nt
	global_load_dwordx4 v[20:23], v[10:11], off offset:-1024 nt
	global_load_dwordx4 v[24:27], v[4:5], off offset:-4096 nt
	global_load_dwordx4 v[28:31], v[4:5], off offset:-3072 nt
	global_load_dwordx4 v[32:35], v[4:5], off offset:-2048 nt
	global_load_dwordx4 v[36:39], v[4:5], off offset:-1024 nt
	global_load_dwordx4 v[40:43], v[4:5], off nt
	s_cmpk_lt_i32 s10, 0x2000
	v_lshl_add_u64 v[4:5], v[4:5], 0, s[8:9]
	s_waitcnt vmcnt(7)
	v_cvt_pk_bf16_f32 v12, v12, v13
	v_cvt_pk_bf16_f32 v13, v14, v15
	global_store_dwordx2 v[2:3], v[12:13], off offset:-3584
	s_waitcnt vmcnt(7)
	v_cvt_pk_bf16_f32 v16, v16, v17
	v_cvt_pk_bf16_f32 v17, v18, v19
	global_store_dwordx2 v[2:3], v[16:17], off offset:-3072
	s_waitcnt vmcnt(7)
	v_cvt_pk_bf16_f32 v20, v20, v21
	v_cvt_pk_bf16_f32 v21, v22, v23
	global_store_dwordx2 v[2:3], v[20:21], off offset:-2560
	s_waitcnt vmcnt(7)
	v_cvt_pk_bf16_f32 v24, v24, v25
	v_cvt_pk_bf16_f32 v25, v26, v27
	global_store_dwordx2 v[2:3], v[24:25], off offset:-2048
	s_waitcnt vmcnt(7)
	v_cvt_pk_bf16_f32 v28, v28, v29
	v_cvt_pk_bf16_f32 v29, v30, v31
	global_store_dwordx2 v[2:3], v[28:29], off offset:-1536
	s_waitcnt vmcnt(7)
	v_cvt_pk_bf16_f32 v32, v32, v33
	v_cvt_pk_bf16_f32 v33, v34, v35
	global_store_dwordx2 v[2:3], v[32:33], off offset:-1024
	s_waitcnt vmcnt(7)
	v_cvt_pk_bf16_f32 v36, v36, v37
	v_cvt_pk_bf16_f32 v37, v38, v39
	global_store_dwordx2 v[2:3], v[36:37], off offset:-512
	s_waitcnt vmcnt(7)
	v_cvt_pk_bf16_f32 v40, v40, v41
	v_cvt_pk_bf16_f32 v41, v42, v43
	global_store_dwordx2 v[2:3], v[40:41], off
	v_lshl_add_u64 v[2:3], v[2:3], 0, s[6:7]
	s_cbranch_scc1 .LBB0_17

.LBB0_264:
	s_sleep 1
	global_load_dword v3, v2, s[10:11] sc1
	s_waitcnt vmcnt(0)
	v_cmp_gt_u32_e32 vcc, 8, v3
	s_cbranch_vccnz .LBB0_264
.LBB0_265:
	s_waitcnt vmcnt(0)
.LBB0_266:
	s_or_b64 exec, exec, s[2:3]
	s_waitcnt vmcnt(0) lgkmcnt(0)
	s_barrier
	s_and_saveexec_b64 s[2:3], s[0:1]
	s_cbranch_execz .LBB0_268
	s_lshl_b32 s0, s35, 3
	s_ashr_i32 s1, s0, 31
	s_waitcnt lgkmcnt(0)
	v_lshl_add_u64 v[2:3], v[0:1], 3, s[4:5]
	s_lshl_b64 s[4:5], s[0:1], 11
	v_lshl_add_u64 v[4:5], v[2:3], 0, s[4:5]
	s_or_b32 s4, s0, 1
	s_ashr_i32 s5, s4, 31
	s_lshl_b64 s[4:5], s[4:5], 11
	v_lshl_add_u64 v[6:7], v[2:3], 0, s[4:5]
	s_or_b32 s4, s0, 2
	s_ashr_i32 s5, s4, 31
	s_lshl_b64 s[4:5], s[4:5], 11
	v_lshl_add_u64 v[8:9], v[2:3], 0, s[4:5]
	s_or_b32 s4, s0, 3
	s_ashr_i32 s5, s4, 31
	s_lshl_b64 s[4:5], s[4:5], 11
	v_lshl_add_u64 v[10:11], v[2:3], 0, s[4:5]
	s_or_b32 s4, s0, 4
	s_ashr_i32 s5, s4, 31
	s_lshl_b64 s[4:5], s[4:5], 11
	v_lshl_add_u64 v[12:13], v[2:3], 0, s[4:5]
	s_or_b32 s4, s0, 5
	global_load_dwordx2 v[4:5], v[4:5], off sc1
	s_ashr_i32 s5, s4, 31
	global_load_dwordx2 v[6:7], v[6:7], off sc1
	s_lshl_b64 s[4:5], s[4:5], 11
	global_load_dwordx2 v[8:9], v[8:9], off sc1
	v_lshl_add_u64 v[14:15], v[2:3], 0, s[4:5]
	s_or_b32 s4, s0, 6
	global_load_dwordx2 v[10:11], v[10:11], off sc1
	s_ashr_i32 s5, s4, 31
	s_or_b32 s0, s0, 7
	global_load_dwordx2 v[12:13], v[12:13], off sc1
	s_lshl_b64 s[4:5], s[4:5], 11
	s_ashr_i32 s1, s0, 31
	global_load_dwordx2 v[14:15], v[14:15], off sc1
	v_lshl_add_u64 v[16:17], v[2:3], 0, s[4:5]
	s_lshl_b64 s[0:1], s[0:1], 11
	global_load_dwordx2 v[16:17], v[16:17], off sc1
	v_lshl_add_u64 v[2:3], v[2:3], 0, s[0:1]
	global_load_dwordx2 v[2:3], v[2:3], off sc1
	s_mov_b32 s0, 0x3a000000
	s_mov_b32 s1, 0xf800000
	v_lshl_add_u32 v0, v0, 3, 0
	s_waitcnt vmcnt(7)
	v_add_f32_e32 v1, 0, v4
	v_add_f32_e32 v4, 0, v5
	s_waitcnt vmcnt(6)
	v_add_f32_e32 v1, v1, v6
	v_add_f32_e32 v4, v4, v7
	s_waitcnt vmcnt(5)
	v_add_f32_e32 v1, v1, v8
	v_add_f32_e32 v4, v4, v9
	s_waitcnt vmcnt(4)
	v_add_f32_e32 v1, v1, v10
	v_add_f32_e32 v4, v4, v11
	s_waitcnt vmcnt(3)
	v_add_f32_e32 v1, v1, v12
	v_add_f32_e32 v4, v4, v13
	s_waitcnt vmcnt(2)
	v_add_f32_e32 v1, v1, v14
	v_add_f32_e32 v4, v4, v15
	s_waitcnt vmcnt(1)
	v_add_f32_e32 v1, v1, v16
	v_add_f32_e32 v4, v4, v17
	s_waitcnt vmcnt(0)
	v_add_f32_e32 v1, v1, v2
	v_mul_f32_e32 v2, 0x3a000000, v1
	v_add_f32_e32 v3, v4, v3
	v_mul_f32_e32 v1, v2, v2
	v_fma_f32 v1, v3, s0, -v1
	v_max_f32_e32 v1, 0, v1
	v_add_f32_e32 v1, 0x3727c5ac, v1
	v_mul_f32_e32 v3, 0x4f800000, v1
	v_cmp_gt_f32_e32 vcc, s1, v1
	v_mov_b32_e32 v4, 0x260
	s_nop 0
	v_cndmask_b32_e32 v1, v1, v3, vcc
	v_sqrt_f32_e32 v3, v1
	s_nop 0
	v_add_u32_e32 v5, -1, v3
	v_add_u32_e32 v6, 1, v3
	v_fma_f32 v7, -v5, v3, v1
	v_fma_f32 v8, -v6, v3, v1
	v_cmp_ge_f32_e64 s[0:1], 0, v7
	s_nop 1
	v_cndmask_b32_e64 v3, v3, v5, s[0:1]
	v_cmp_lt_f32_e64 s[0:1], 0, v8
	s_nop 1
	v_cndmask_b32_e64 v3, v3, v6, s[0:1]
	v_mul_f32_e32 v5, 0x37800000, v3
	v_cndmask_b32_e32 v3, v3, v5, vcc
	v_cmp_class_f32_e32 vcc, v1, v4
	s_nop 1
	v_cndmask_b32_e32 v1, v3, v1, vcc
	v_div_scale_f32 v3, s[0:1], v1, v1, 1.0
	v_rcp_f32_e32 v4, v3
	v_div_scale_f32 v5, vcc, 1.0, v1, 1.0
	v_fma_f32 v6, -v3, v4, 1.0
	v_fmac_f32_e32 v4, v6, v4
	v_mul_f32_e32 v6, v5, v4
	v_fma_f32 v7, -v3, v6, v5
	v_fmac_f32_e32 v6, v7, v4
	v_fma_f32 v3, -v3, v6, v5
	v_div_fmas_f32 v3, v3, v4, v6
	v_div_fixup_f32 v3, v3, v1, 1.0
	ds_write_b64 v0, v[2:3] offset:8192

.LBB0_451:
	s_add_i32 s18, s34, 64
	s_sub_i32 s19, 0xfbf, s34
	s_and_b64 s[16:17], s[2:3], exec
	s_cselect_b32 s16, s18, s19
	s_ashr_i32 s17, s16, 31
	s_lshl_b64 s[16:17], s[16:17], 12
	s_sub_i32 s18, 0xfbf, s51
	s_add_i32 s19, s34, 0x41
	global_load_dword v48, v[24:25], off offset:32
	v_lshl_add_u64 v[24:25], v[64:65], 0, s[16:17]
	s_and_b64 s[16:17], s[2:3], exec
	s_cselect_b32 s16, s19, s18
	s_ashr_i32 s17, s16, 31
	s_lshl_b64 s[16:17], s[16:17], 12
	s_sub_i32 s18, 0xfbf, s63
	s_add_i32 s19, s34, 0x42
	v_lshl_add_u64 v[28:29], v[64:65], 0, s[16:17]
	s_and_b64 s[16:17], s[2:3], exec
	s_cselect_b32 s16, s19, s18
	s_ashr_i32 s17, s16, 31
	s_lshl_b64 s[16:17], s[16:17], 12
	s_sub_i32 s18, 0xfbf, s62
	s_add_i32 s19, s34, 0x43
	v_lshl_add_u64 v[30:31], v[64:65], 0, s[16:17]
	s_and_b64 s[16:17], s[2:3], exec
	s_cselect_b32 s16, s19, s18
	s_ashr_i32 s17, s16, 31
	s_lshl_b64 s[16:17], s[16:17], 12
	s_sub_i32 s18, 0xfbf, s60
	s_add_i32 s19, s34, 0x44
	v_lshl_add_u64 v[32:33], v[64:65], 0, s[16:17]
	s_and_b64 s[16:17], s[2:3], exec
	s_cselect_b32 s16, s19, s18
	s_ashr_i32 s17, s16, 31
	s_lshl_b64 s[16:17], s[16:17], 12
	s_sub_i32 s18, 0xfbf, s59
	s_add_i32 s19, s34, 0x45
	global_load_dword v151, v[24:25], off
	global_load_dword v152, v[24:25], off offset:2048
	global_load_dword v153, v[28:29], off
	global_load_dword v154, v[28:29], off offset:2048
	global_load_dword v157, v[30:31], off
	global_load_dword v158, v[30:31], off offset:2048
	global_load_dword v159, v[32:33], off
	global_load_dword v160, v[32:33], off offset:2048
	v_lshl_add_u64 v[24:25], v[64:65], 0, s[16:17]
	s_and_b64 s[16:17], s[2:3], exec
	s_cselect_b32 s16, s19, s18
	s_ashr_i32 s17, s16, 31
	s_lshl_b64 s[16:17], s[16:17], 12
	s_sub_i32 s18, 0xfbf, s58
	s_add_i32 s19, s34, 0x46
	v_lshl_add_u64 v[28:29], v[64:65], 0, s[16:17]
	s_and_b64 s[16:17], s[2:3], exec
	s_cselect_b32 s16, s19, s18
	s_ashr_i32 s17, s16, 31
	s_lshl_b64 s[16:17], s[16:17], 12
	s_sub_i32 s18, 0xfbf, s57
	s_add_i32 s19, s34, 0x47
	v_lshl_add_u64 v[30:31], v[64:65], 0, s[16:17]
	s_and_b64 s[16:17], s[2:3], exec
	s_cselect_b32 s16, s19, s18
	s_ashr_i32 s17, s16, 31
	s_lshl_b64 s[16:17], s[16:17], 12
	s_sub_i32 s18, 0xfbf, s56
	s_add_i32 s19, s34, 0x48
	v_lshl_add_u64 v[32:33], v[64:65], 0, s[16:17]
	s_and_b64 s[16:17], s[2:3], exec
	s_cselect_b32 s16, s19, s18
	s_ashr_i32 s17, s16, 31
	s_lshl_b64 s[16:17], s[16:17], 12
	s_sub_i32 s18, 0xfbf, s55
	s_add_i32 s19, s34, 0x49
	global_load_dword v161, v[24:25], off
	global_load_dword v162, v[24:25], off offset:2048
	global_load_dword v164, v[28:29], off
	global_load_dword v165, v[28:29], off offset:2048
	global_load_dword v169, v[30:31], off
	global_load_dword v171, v[30:31], off offset:2048
	global_load_dword v180, v[32:33], off
	global_load_dword v181, v[32:33], off offset:2048
	v_lshl_add_u64 v[24:25], v[64:65], 0, s[16:17]
	s_and_b64 s[16:17], s[2:3], exec
	s_cselect_b32 s16, s19, s18
	s_ashr_i32 s17, s16, 31
	s_lshl_b64 s[16:17], s[16:17], 12
	s_sub_i32 s18, 0xfbf, s54
	s_add_i32 s19, s34, 0x4a
	v_lshl_add_u64 v[28:29], v[64:65], 0, s[16:17]
	s_and_b64 s[16:17], s[2:3], exec
	s_cselect_b32 s16, s19, s18
	s_ashr_i32 s17, s16, 31
	s_lshl_b64 s[16:17], s[16:17], 12
	s_sub_i32 s18, 0xfbf, s53
	s_add_i32 s19, s34, 0x4b
	v_lshl_add_u64 v[30:31], v[64:65], 0, s[16:17]
	s_and_b64 s[16:17], s[2:3], exec
	s_cselect_b32 s16, s19, s18
	s_ashr_i32 s17, s16, 31
	s_lshl_b64 s[16:17], s[16:17], 12
	s_sub_i32 s18, 0xfbf, s52
	s_add_i32 s19, s34, 0x4c
	v_lshl_add_u64 v[32:33], v[64:65], 0, s[16:17]
	s_and_b64 s[16:17], s[2:3], exec
	s_cselect_b32 s16, s19, s18
	s_ashr_i32 s17, s16, 31
	s_lshl_b64 s[16:17], s[16:17], 12
	s_sub_i32 s18, 0xfbf, s50
	s_add_i32 s19, s34, 0x4d
	global_load_dword v190, v[24:25], off
	global_load_dword v191, v[24:25], off offset:2048
	global_load_dword v192, v[28:29], off
	global_load_dword v193, v[28:29], off offset:2048
	global_load_dword v194, v[30:31], off
	global_load_dword v195, v[30:31], off offset:2048
	global_load_dword v196, v[32:33], off
	global_load_dword v197, v[32:33], off offset:2048
	v_lshl_add_u64 v[24:25], v[64:65], 0, s[16:17]
	s_and_b64 s[16:17], s[2:3], exec
	s_cselect_b32 s16, s19, s18
	s_ashr_i32 s17, s16, 31
	s_lshl_b64 s[16:17], s[16:17], 12
	s_sub_i32 s18, 0xfbf, s48
	s_add_i32 s19, s34, 0x4e
	v_lshl_add_u64 v[28:29], v[64:65], 0, s[16:17]
	s_and_b64 s[16:17], s[2:3], exec
	s_cselect_b32 s16, s19, s18
	s_ashr_i32 s17, s16, 31
	s_lshl_b64 s[16:17], s[16:17], 12
	s_sub_i32 s18, 0xfbf, s47
	s_add_i32 s19, s34, 0x4f
	v_lshl_add_u64 v[30:31], v[64:65], 0, s[16:17]
	s_and_b64 s[16:17], s[2:3], exec
	s_cselect_b32 s16, s19, s18
	s_ashr_i32 s17, s16, 31
	s_lshl_b64 s[16:17], s[16:17], 12
	v_lshl_add_u64 v[32:33], v[64:65], 0, s[16:17]
	global_load_dword v198, v[24:25], off
	global_load_dword v199, v[24:25], off offset:2048
	global_load_dword v200, v[28:29], off
	global_load_dword v201, v[28:29], off offset:2048
	global_load_dword v202, v[30:31], off
	global_load_dword v203, v[30:31], off offset:2048
	global_load_dword v204, v[32:33], off
	global_load_dword v205, v[32:33], off offset:2048
	v_xor_b32_e32 v0, v26, v63
	v_lshl_add_u32 v166, v0, 4, v73
	v_lshlrev_b32_e32 v0, 1, v56
	v_and_b32_e32 v24, 64, v108
	v_lshl_add_u64 v[68:69], s[6:7], 0, v[0:1]
	s_and_b32 s6, s34, 48
	v_or_b32_e32 v0, s34, v50
	v_or3_b32 v27, s6, v58, v24
	s_lshr_b32 s6, s35, 1
	s_lshl_b32 s16, s46, 1
	v_mul_lo_u32 v25, v0, s78
	v_lshl_or_b32 v26, s49, 4, v50
	v_mul_lo_u32 v28, v0, s37
	v_mov_b32_e32 v0, s75
	s_and_b32 s6, s6, 0xfffffe0
	s_andn2_b32 s35, s35, 63
	v_mad_u32_u24 v168, v26, s37, v0
	v_or_b32_e32 v0, v24, v75
	v_or_b32_e32 v24, s6, v50
	s_and_b64 s[6:7], s[2:3], exec
	s_cselect_b32 s6, s77, s33
	s_cselect_b32 s7, s76, s36
	s_lshl_b64 s[4:5], s[4:5], 1
	s_add_u32 s4, s7, s4
	s_addc_u32 s5, s6, s5
	s_lshl_b32 s6, s15, 1
	s_add_u32 s4, s4, s6
	s_addc_u32 s5, s5, 0
	v_lshl_add_u32 v163, v23, 1, 0
	s_movk_i32 s17, 0x8e
	s_add_u32 s4, s4, s14
	v_mad_u32_u24 v23, v23, s17, v163
	v_lshlrev_b32_e32 v170, 2, v0
	v_xor_b32_e32 v0, s16, v63
	s_addc_u32 s5, s5, 0
	s_lshl_b32 s6, s49, 5
	v_lshl_add_u32 v173, v0, 4, v23
	v_bitop3_b32 v0, s16, v63, 1 bitop3:0x36
	s_add_u32 s4, s4, s6
	v_lshl_add_u32 v174, v0, 4, v23
	s_addc_u32 s5, s5, 0
	v_lshlrev_b32_e32 v0, 1, v50
	v_add_u32_e32 v172, s35, v78
	v_lshlrev_b32_e32 v176, 2, v27
	v_lshl_add_u64 v[70:71], s[4:5], 0, v[0:1]
	v_mul_lo_u32 v0, v24, s37
	s_mov_b32 s18, 0
	s_mov_b32 s19, 2
	v_mul_u32_u24_e32 v167, 0x210, v26
	s_mul_i32 s20, s46, 0x2100
	s_mul_i32 s21, s51, 0x210
	v_not_b32_e32 v175, v127
	v_or_b32_e32 v177, 4, v176
	v_or_b32_e32 v178, 8, v176
	v_or_b32_e32 v179, 12, v176
	v_add_u32_e32 v0, 0, v0
	s_sub_i32 s24, 0, s34
	v_or_b32_e32 v182, s6, v74
	v_add_u32_e32 v183, s34, v58
	v_subrev_u32_e32 v184, s34, v104
	v_subrev_u32_e32 v185, s34, v83
	v_subrev_u32_e32 v186, s6, v106
	s_mov_b32 s25, 62
	v_add_u32_e32 v187, v99, v25
	v_add_u32_e32 v188, v76, v28
	v_add_u32_e32 v189, v172, v85
	s_mov_b32 s26, 0
	v_mov_b32_e32 v23, v22
	v_mov_b32_e32 v24, v22
	v_mov_b32_e32 v25, v22
	v_mov_b32_e32 v30, v22
	v_mov_b32_e32 v31, v22
	v_mov_b32_e32 v32, v22
	v_mov_b32_e32 v33, v22
	v_mov_b32_e32 v26, v22
	v_mov_b32_e32 v27, v22
	v_mov_b32_e32 v28, v22
	v_mov_b32_e32 v29, v22
	v_mov_b32_e32 v34, v22
	v_mov_b32_e32 v35, v22
	v_mov_b32_e32 v36, v22
	v_mov_b32_e32 v37, v22
	v_mov_b32_e32 v38, v22
	v_mov_b32_e32 v39, v22
	v_mov_b32_e32 v40, v22
	v_mov_b32_e32 v41, v22
	v_mov_b32_e32 v42, v22
	v_mov_b32_e32 v43, v22
	v_mov_b32_e32 v44, v22
	v_mov_b32_e32 v45, v22
	v_readfirstlane_b32 s58, v64
	v_readfirstlane_b32 s59, v65
	s_lshr_b32 s36, s35, 6
	s_and_b32 s36, s36, 1
	s_lshl_b32 s36, s36, 8
	s_sub_u32 s58, s58, s36
	s_subb_u32 s59, s59, 0
	v_lshlrev_b32_e32 v89, 2, v220
	v_add_u32_e32 v89, s36, v89
	s_cmp_eq_u32 s61, 0
	s_cselect_b32 s57, 0, -1
	s_xor_b32 s56, s57, 0x40000
	s_sub_i32 s56, s56, s57
	s_xor_b32 s36, s57, 0x2000
	s_sub_i32 s36, s36, s57
	s_and_b32 s37, s57, 0xe000
	s_and_b32 s40, s57, 0x1000
	s_andn2_b32 s41, 0x1000, s57
	s_add_i32 s38, s34, 0x80
	s_sub_i32 s39, 0xf70, s34
	s_cmp_eq_u32 s61, 0
	s_cselect_b32 s38, s38, s39
	s_lshl_b32 s38, s38, 12
	s_add_u32 s58, s58, s38
	s_addc_u32 s59, s59, 0
	s_add_u32 s52, s58, s40
	s_addc_u32 s53, s59, 0
	s_add_u32 s54, s58, s41
	s_addc_u32 s55, s59, 0
	v_add_u32_e32 v89, s37, v89
	v_add_u32_e32 v90, s36, v89
	v_add_u32_e32 v91, s36, v90
	v_add_u32_e32 v92, s36, v91
	v_add_u32_e32 v93, s36, v92
	v_add_u32_e32 v94, s36, v93
	v_add_u32_e32 v95, s36, v94
	v_add_u32_e32 v96, s36, v95
	v_readfirstlane_b32 s36, v68
	v_readfirstlane_b32 s37, v69
	s_cmp_eq_u32 s61, 0
	s_cselect_b32 s58, 64, 0xf80
	s_mul_i32 s59, s58, 0x4800
	s_add_u32 s36, s36, s59
	s_addc_u32 s37, s37, 0
	s_lshl_b32 s59, s58, 6
	s_add_u32 s38, s8, s59
	s_addc_u32 s39, s9, 0
	s_xor_b32 s40, s57, 0x120000
	s_sub_i32 s40, s40, s57
	s_xor_b32 s41, s57, 0x1000
	s_sub_i32 s41, s41, s57
	s_and_b32 s58, s57, 64
	s_xor_b32 s59, s57, 0x4800
	s_sub_i32 s59, s59, s57
	s_xor_b32 s60, s57, 64
	s_sub_i32 s60, s60, s57
	v_xor_b32_e32 v73, s57, v182
	v_add_u32_e32 v73, s58, v73
	v_mul_u32_u24_e32 v97, 0x4800, v73
	v_lshl_add_u32 v97, v50, 2, v97
	v_lshlrev_b32_e32 v50, 6, v73
	v_add_u32_e32 v98, s59, v97
	v_add_u32_e32 v99, s59, v98
	v_add_u32_e32 v100, s59, v99
	v_add_u32_e32 v101, s59, v100
	v_add_u32_e32 v102, s59, v101
	v_add_u32_e32 v103, s59, v102
	v_add_u32_e32 v104, s59, v103
	v_add_u32_e32 v51, s60, v50
	v_add_u32_e32 v52, s60, v51
	v_add_u32_e32 v53, s60, v52
	v_add_u32_e32 v54, s60, v53
	v_add_u32_e32 v55, s60, v54
	v_add_u32_e32 v56, s60, v55
	v_add_u32_e32 v57, s60, v56
	v_xor_b32_e32 v73, s57, v220
	v_add_u32_e32 v73, s58, v73
	v_lshlrev_b32_e32 v73, 6, v73
	s_waitcnt vmcnt(32)
	s_branch .LBB0_453

.LBB0_453:
	s_waitcnt vmcnt(36)
	ds_bpermute_b32 v224, v109, v48
	v_cndmask_b32_e64 v46, 0, 1, s[12:13]
	v_cmp_ne_u32_e64 s[4:5], 1, v46
	s_andn2_b64 vcc, exec, s[12:13]
	s_cbranch_vccnz .LBB0_455
	v_cvt_pk_bf16_f32 v46, v148, s0
	ds_write_b16 v72, v46 offset:4608

.LBB0_459:
	s_and_b64 vcc, exec, s[6:7]
	s_cbranch_vccnz .LBB0_461
	global_load_dword v2, v97, s[36:37] nt
	global_load_dword v10, v50, s[38:39]
	global_load_dword v3, v98, s[36:37] nt
	global_load_dword v11, v51, s[38:39]
	global_load_dword v4, v99, s[36:37] nt
	global_load_dword v12, v52, s[38:39]
	global_load_dword v5, v100, s[36:37] nt
	global_load_dword v13, v53, s[38:39]
	global_load_dword v6, v101, s[36:37] nt
	global_load_dword v14, v54, s[38:39]
	global_load_dword v7, v102, s[36:37] nt
	global_load_dword v15, v55, s[38:39]
	global_load_dword v8, v103, s[36:37] nt
	global_load_dword v16, v56, s[38:39]
	global_load_dword v9, v104, s[36:37] nt
	global_load_dword v17, v57, s[38:39]
.LBB0_461:
	s_add_i32 s28, s19, -1
	s_and_b64 s[16:17], s[2:3], exec
	s_cselect_b32 s16, s28, s25
	s_mov_b32 s17, s22
	s_lshl_b64 s[16:17], s[16:17], 14
	v_lshl_add_u64 v[18:19], v[66:67], 0, s[16:17]
	global_load_dwordx4 v[18:21], v[18:19], off
	s_and_b64 vcc, exec, s[4:5]
	s_cbranch_vccnz .LBB0_463
	global_load_dword v148, v73, s[38:39]
.LBB0_463:
	global_load_dword v207, v73, s[38:39] offset:32
	s_add_u32 s36, s36, s40
	s_addc_u32 s37, s37, s57
	s_add_u32 s38, s38, s41
	s_addc_u32 s39, s39, s57
	ds_read_b128 v[226:229], v187
	v_add_u32_e32 v46, v79, v167
	ds_read_b128 v[230:233], v46
	ds_read_b128 v[234:237], v80
	s_waitcnt lgkmcnt(1)
	v_mfma_f32_16x16x32_bf16 v[230:233], v[226:229], v[230:233], 0
	global_load_dword v113, v89, s[52:53]
	s_waitcnt lgkmcnt(0)
	v_mfma_f32_16x16x32_bf16 v[226:229], v[226:229], v[234:237], 0
	global_load_dword v114, v89, s[52:53] offset:2048
	ds_read_b128 v[234:237], v187 offset:64
	ds_read_b128 v[238:241], v46 offset:64
	s_waitcnt lgkmcnt(0)
	v_mfma_f32_16x16x32_bf16 v[230:233], v[234:237], v[238:241], v[230:233]
	global_load_dword v115, v89, s[54:55]
	ds_read_b128 v[238:241], v80 offset:64
	s_waitcnt lgkmcnt(0)
	v_mfma_f32_16x16x32_bf16 v[226:229], v[234:237], v[238:241], v[226:229]
	global_load_dword v116, v89, s[54:55] offset:2048
	ds_read_b128 v[234:237], v187 offset:128
	ds_read_b128 v[238:241], v46 offset:128
	s_waitcnt lgkmcnt(0)
	v_mfma_f32_16x16x32_bf16 v[230:233], v[234:237], v[238:241], v[230:233]
	global_load_dword v117, v90, s[52:53]
	ds_read_b128 v[238:241], v80 offset:128
	s_waitcnt lgkmcnt(0)
	v_mfma_f32_16x16x32_bf16 v[226:229], v[234:237], v[238:241], v[226:229]
	global_load_dword v118, v90, s[52:53] offset:2048
	ds_read_b128 v[234:237], v187 offset:192
	ds_read_b128 v[238:241], v46 offset:192
	s_waitcnt lgkmcnt(0)
	v_mfma_f32_16x16x32_bf16 v[230:233], v[234:237], v[238:241], v[230:233]
	global_load_dword v119, v90, s[54:55]
	ds_read_b128 v[238:241], v80 offset:192
	s_waitcnt lgkmcnt(0)
	v_mfma_f32_16x16x32_bf16 v[226:229], v[234:237], v[238:241], v[226:229]
	global_load_dword v120, v90, s[54:55] offset:2048
	ds_read_b128 v[234:237], v187 offset:256
	ds_read_b128 v[238:241], v46 offset:256
	s_waitcnt lgkmcnt(0)
	v_mfma_f32_16x16x32_bf16 v[230:233], v[234:237], v[238:241], v[230:233]
	global_load_dword v121, v91, s[52:53]
	ds_read_b128 v[238:241], v80 offset:256
	s_waitcnt lgkmcnt(0)
	v_mfma_f32_16x16x32_bf16 v[226:229], v[234:237], v[238:241], v[226:229]
	global_load_dword v122, v91, s[52:53] offset:2048
	ds_read_b128 v[234:237], v187 offset:320
	ds_read_b128 v[238:241], v46 offset:320
	s_waitcnt lgkmcnt(0)
	v_mfma_f32_16x16x32_bf16 v[230:233], v[234:237], v[238:241], v[230:233]
	global_load_dword v123, v91, s[54:55]
	ds_read_b128 v[238:241], v80 offset:320
	s_waitcnt lgkmcnt(0)
	v_mfma_f32_16x16x32_bf16 v[226:229], v[234:237], v[238:241], v[226:229]
	global_load_dword v124, v91, s[54:55] offset:2048
	ds_read_b128 v[234:237], v187 offset:384
	ds_read_b128 v[238:241], v46 offset:384
	s_waitcnt lgkmcnt(0)
	v_mfma_f32_16x16x32_bf16 v[230:233], v[234:237], v[238:241], v[230:233]
	global_load_dword v125, v92, s[52:53]
	ds_read_b128 v[238:241], v80 offset:384
	s_waitcnt lgkmcnt(0)
	v_mfma_f32_16x16x32_bf16 v[226:229], v[234:237], v[238:241], v[226:229]
	global_load_dword v126, v92, s[52:53] offset:2048
	ds_read_b128 v[234:237], v187 offset:448
	ds_read_b128 v[238:241], v46 offset:448
	s_waitcnt lgkmcnt(0)
	v_mfma_f32_16x16x32_bf16 v[230:233], v[234:237], v[238:241], v[230:233]
	global_load_dword v134, v92, s[54:55]
	ds_read_b128 v[238:241], v80 offset:448
	s_waitcnt lgkmcnt(0)
	v_mfma_f32_16x16x32_bf16 v[226:229], v[234:237], v[238:241], v[226:229]
	global_load_dword v135, v92, s[54:55] offset:2048
	ds_bpermute_b32 v46, v176, v48
	v_add_u32_e32 v206, v77, v75
	v_add_u32_e32 v217, s18, v183
	s_waitcnt lgkmcnt(0)
	v_mul_f32_e32 v46, 0x3fb8aa3b, v46
	v_exp_f32_e32 v218, v46
	ds_bpermute_b32 v46, v177, v48
	s_waitcnt lgkmcnt(0)
	v_mul_f32_e32 v46, 0x3fb8aa3b, v46
	v_exp_f32_e32 v219, v46
	ds_bpermute_b32 v46, v178, v48
	v_pk_mul_f32 v[226:227], v[226:227], v[218:219]
	s_waitcnt lgkmcnt(0)
	v_mul_f32_e32 v46, 0x3fb8aa3b, v46
	v_exp_f32_e32 v222, v46
	ds_bpermute_b32 v46, v179, v48
	s_waitcnt lgkmcnt(0)
	v_mul_f32_e32 v46, 0x3fb8aa3b, v46
	v_exp_f32_e32 v223, v46
	v_pk_mul_f32 v[46:47], v[230:231], v[218:219]
	v_add_u32_e32 v218, v168, v81
	ds_read_b128 v[234:237], v218
	v_pk_mul_f32 v[48:49], v[232:233], v[222:223]
	ds_read_b128 v[230:233], v188
	v_pk_mul_f32 v[228:229], v[228:229], v[222:223]
	v_add_u32_e32 v219, v168, v82
	v_add_u32_e32 v222, s26, v185
	s_waitcnt lgkmcnt(0)
	v_mfma_f32_16x16x32_bf16 v[46:49], v[230:233], v[234:237], v[46:49]
	global_load_dword v136, v93, s[52:53]
	ds_read_b128 v[234:237], v206
	s_waitcnt lgkmcnt(0)
	v_mfma_f32_16x16x32_bf16 v[226:229], v[230:233], v[234:237], v[226:229]
	global_load_dword v137, v93, s[52:53] offset:2048
	ds_read_b128 v[230:233], v188 offset:64
	ds_read_b128 v[234:237], v219
	s_waitcnt lgkmcnt(0)
	v_mfma_f32_16x16x32_bf16 v[46:49], v[230:233], v[234:237], v[46:49]
	global_load_dword v138, v93, s[54:55]
	ds_read_b128 v[234:237], v110
	s_waitcnt lgkmcnt(0)
	v_mfma_f32_16x16x32_bf16 v[226:229], v[230:233], v[234:237], v[226:229]
	global_load_dword v139, v93, s[54:55] offset:2048
	v_cndmask_b32_e64 v230, v222, v217, s[2:3]
	v_ashrrev_i32_e32 v231, 31, v230
	v_lshlrev_b64 v[230:231], 12, v[230:231]
	s_nop 4
	ds_bpermute_b32 v223, v170, v226
	v_lshl_add_u64 v[230:231], v[70:71], 0, v[230:231]
	s_waitcnt lgkmcnt(0)
	v_max_f32_e64 v223, |v223|, |v223|
	v_max_f32_e32 v223, 1.0, v223
	v_div_scale_f32 v225, s[16:17], v223, v223, v46
	v_rcp_f32_e32 v226, v225
	s_nop 0
	v_fma_f32 v232, -v225, v226, 1.0
	v_fmac_f32_e32 v226, v232, v226
	v_div_scale_f32 v232, vcc, v46, v223, v46
	v_mul_f32_e32 v233, v232, v226
	v_fma_f32 v234, -v225, v233, v232
	v_fmac_f32_e32 v233, v234, v226
	v_fma_f32 v225, -v225, v233, v232
	v_div_fmas_f32 v225, v225, v226, v233
	v_div_fixup_f32 v46, v225, v223, v46
	v_cvt_pk_bf16_f32 v46, v46, s0
	global_store_short v[230:231], v46, off offset:2048
	ds_bpermute_b32 v46, v170, v227
	v_add_u32_e32 v223, -1, v222
	v_add_u32_e32 v225, 1, v217
	v_cndmask_b32_e64 v226, v223, v225, s[2:3]
	v_ashrrev_i32_e32 v227, 31, v226
	s_waitcnt lgkmcnt(0)
	v_max_f32_e64 v46, |v46|, |v46|
	v_max_f32_e32 v46, 1.0, v46
	v_div_scale_f32 v223, s[16:17], v46, v46, v47
	v_rcp_f32_e32 v225, v223
	s_nop 0
	v_fma_f32 v230, -v223, v225, 1.0
	v_fmac_f32_e32 v225, v230, v225
	v_div_scale_f32 v230, vcc, v47, v46, v47
	v_mul_f32_e32 v231, v230, v225
	v_fma_f32 v232, -v223, v231, v230
	v_fmac_f32_e32 v231, v232, v225
	v_fma_f32 v223, -v223, v231, v230
	v_div_fmas_f32 v223, v223, v225, v231
	ds_bpermute_b32 v225, v170, v228
	v_div_fixup_f32 v46, v223, v46, v47
	v_cvt_pk_bf16_f32 v223, v46, s0
	v_lshlrev_b64 v[46:47], 12, v[226:227]
	v_lshl_add_u64 v[46:47], v[70:71], 0, v[46:47]
	s_waitcnt lgkmcnt(0)
	v_max_f32_e64 v225, |v225|, |v225|
	v_max_f32_e32 v225, 1.0, v225
	v_div_scale_f32 v226, s[16:17], v225, v225, v48
	v_rcp_f32_e32 v227, v226
	global_store_short v[46:47], v223, off offset:2048
	v_add_u32_e32 v223, s26, v184
	v_add_u32_e32 v46, 0xffd, v223
	v_fma_f32 v228, -v226, v227, 1.0
	v_fmac_f32_e32 v227, v228, v227
	v_div_scale_f32 v228, vcc, v48, v225, v48
	v_mul_f32_e32 v230, v228, v227
	v_fma_f32 v231, -v226, v230, v228
	v_add_u32_e32 v47, 2, v217
	v_fmac_f32_e32 v230, v231, v227
	v_cndmask_b32_e64 v46, v46, v47, s[2:3]
	v_fma_f32 v226, -v226, v230, v228
	v_ashrrev_i32_e32 v47, 31, v46
	v_div_fmas_f32 v226, v226, v227, v230
	v_div_fixup_f32 v48, v226, v225, v48
	v_lshlrev_b64 v[46:47], 12, v[46:47]
	v_cvt_pk_bf16_f32 v48, v48, s0
	v_lshl_add_u64 v[46:47], v[70:71], 0, v[46:47]
	global_store_short v[46:47], v48, off offset:2048
	ds_bpermute_b32 v48, v170, v229
	v_add_u32_e32 v46, 0xffc, v223
	v_add_u32_e32 v47, 3, v217
	v_cndmask_b32_e64 v46, v46, v47, s[2:3]
	v_ashrrev_i32_e32 v47, 31, v46
	s_waitcnt lgkmcnt(0)
	v_max_f32_e64 v48, |v48|, |v48|
	v_max_f32_e32 v48, 1.0, v48
	v_div_scale_f32 v225, s[16:17], v48, v48, v49
	v_rcp_f32_e32 v226, v225
	v_lshlrev_b64 v[46:47], 12, v[46:47]
	v_lshl_add_u64 v[46:47], v[70:71], 0, v[46:47]
	v_fma_f32 v227, -v225, v226, 1.0
	v_fmac_f32_e32 v226, v227, v226
	v_div_scale_f32 v227, vcc, v49, v48, v49
	v_mul_f32_e32 v228, v227, v226
	v_fma_f32 v229, -v225, v228, v227
	v_fmac_f32_e32 v228, v229, v226
	v_fma_f32 v225, -v225, v228, v227
	v_div_fmas_f32 v225, v225, v226, v228
	v_div_fixup_f32 v48, v225, v48, v49
	v_cvt_pk_bf16_f32 v48, v48, s0
	global_store_short v[46:47], v48, off offset:2048
	v_mul_f32_e32 v46, 0x3fb8aa3b, v224
	v_add_u32_e32 v224, v0, v81
	v_exp_f32_e32 v46, v46
	ds_read_b128 v[226:229], v224 offset:33792
	ds_read_b128 v[230:233], v111
	v_add_u32_e32 v49, v0, v82
	v_add_u32_e32 v225, v84, v82
	v_pk_mul_f32 v[44:45], v[44:45], v[46:47] op_sel_hi:[1,0]
	v_pk_mul_f32 v[42:43], v[42:43], v[46:47] op_sel_hi:[1,0]
	v_pk_mul_f32 v[40:41], v[40:41], v[46:47] op_sel_hi:[1,0]
	v_pk_mul_f32 v[38:39], v[38:39], v[46:47] op_sel_hi:[1,0]
	s_waitcnt lgkmcnt(0)
	v_mfma_f32_16x16x32_bf16 v[42:45], v[226:229], v[230:233], v[42:45]
	global_load_dword v140, v94, s[52:53]
	ds_read_b128 v[226:229], v49 offset:33792
	ds_read_b128 v[230:233], v225
	v_pk_mul_f32 v[36:37], v[36:37], v[46:47] op_sel_hi:[1,0]
	s_waitcnt lgkmcnt(0)
	v_mfma_f32_16x16x32_bf16 v[42:45], v[226:229], v[230:233], v[42:45]
	global_load_dword v141, v94, s[52:53] offset:2048
	v_mul_f32_e64 v34, v34, v46
	v_mul_f32_e64 v35, v35, v46
	s_nop 5
	v_cvt_pk_bf16_f32 v226, v42, v43
	v_cvt_pk_bf16_f32 v227, v44, v45
	ds_write_b64 v189, v[226:227] offset:17952
	v_add_u32_e32 v226, v86, v81
	ds_read_b128 v[228:231], v49 offset:33792
	ds_read_b128 v[232:235], v224 offset:33792
	ds_read_b128 v[236:239], v226
	v_add_u32_e32 v227, v86, v82
	s_waitcnt lgkmcnt(0)
	v_mfma_f32_16x16x32_bf16 v[38:41], v[232:235], v[236:239], v[38:41]
	global_load_dword v142, v94, s[54:55]
	ds_read_b128 v[232:235], v227
	s_waitcnt lgkmcnt(0)
	v_mfma_f32_16x16x32_bf16 v[38:41], v[228:231], v[232:235], v[38:41]
	global_load_dword v143, v94, s[54:55] offset:2048
	s_nop 7
	v_cvt_pk_bf16_f32 v228, v38, v39
	v_cvt_pk_bf16_f32 v229, v40, v41
	ds_write_b64 v189, v[228:229] offset:26400
	ds_read_b128 v[228:231], v49 offset:33792
	ds_read_b128 v[232:235], v224 offset:33792
	ds_read_b128 v[236:239], v206
	s_waitcnt lgkmcnt(0)
	v_mfma_f32_16x16x32_bf16 v[34:37], v[232:235], v[236:239], v[34:37]
	global_load_dword v144, v95, s[52:53]
	ds_read_b128 v[232:235], v110
	s_waitcnt lgkmcnt(0)
	v_mfma_f32_16x16x32_bf16 v[34:37], v[228:231], v[232:235], v[34:37]
	global_load_dword v145, v95, s[52:53] offset:2048
	s_and_saveexec_b64 s[16:17], s[0:1]
	s_nop 6
	v_cvt_pk_bf16_f32 v228, v34, v35
	v_cvt_pk_bf16_f32 v229, v36, v37
	ds_write_b64 v172, v[228:229] offset:34848
	s_or_b64 exec, exec, s[16:17]
	ds_read_b128 v[228:231], v224 offset:36096
	ds_read_b128 v[232:235], v111
	ds_read_b128 v[236:239], v49 offset:36096
	v_mov_b32_e32 v47, v46
	v_mov_b32_e32 v240, v46
	v_mov_b32_e32 v241, v46
	v_pk_mul_f32 v[28:29], v[28:29], v[240:241]
	v_pk_mul_f32 v[26:27], v[26:27], v[46:47]
	v_pk_mul_f32 v[32:33], v[32:33], v[240:241]
	v_pk_mul_f32 v[30:31], v[30:31], v[46:47]
	s_waitcnt lgkmcnt(1)
	v_mfma_f32_16x16x32_bf16 v[26:29], v[228:231], v[232:235], v[26:29]
	global_load_dword v146, v95, s[54:55]
	ds_read_b128 v[228:231], v225
	v_pk_mul_f32 v[24:25], v[24:25], v[240:241]
	v_pk_mul_f32 v[22:23], v[22:23], v[46:47]
	s_waitcnt lgkmcnt(0)
	v_mfma_f32_16x16x32_bf16 v[26:29], v[236:239], v[228:231], v[26:29]
	global_load_dword v147, v95, s[54:55] offset:2048
	s_nop 7
	v_cvt_pk_bf16_f32 v228, v26, v27
	v_cvt_pk_bf16_f32 v229, v28, v29
	ds_write_b64 v189, v[228:229] offset:17984
	ds_read_b128 v[228:231], v224 offset:36096
	ds_read_b128 v[232:235], v226
	ds_read_b128 v[236:239], v227
	s_waitcnt lgkmcnt(1)
	v_mfma_f32_16x16x32_bf16 v[30:33], v[228:231], v[232:235], v[30:33]
	global_load_dword v149, v96, s[52:53]
	ds_read_b128 v[228:231], v49 offset:36096
	s_waitcnt lgkmcnt(0)
	v_mfma_f32_16x16x32_bf16 v[30:33], v[228:231], v[236:239], v[30:33]
	global_load_dword v150, v96, s[52:53] offset:2048
	s_nop 7
	v_cvt_pk_bf16_f32 v228, v30, v31
	v_cvt_pk_bf16_f32 v229, v32, v33
	ds_write_b64 v189, v[228:229] offset:26432
	ds_read_b128 v[228:231], v224 offset:36096
	ds_read_b128 v[232:235], v206
	ds_read_b128 v[236:239], v110
	s_waitcnt lgkmcnt(1)
	v_mfma_f32_16x16x32_bf16 v[22:25], v[228:231], v[232:235], v[22:25]
	global_load_dword v155, v96, s[54:55]
	ds_read_b128 v[228:231], v49 offset:36096
	s_waitcnt lgkmcnt(0)
	v_mfma_f32_16x16x32_bf16 v[22:25], v[228:231], v[236:239], v[22:25]
	global_load_dword v156, v96, s[54:55] offset:2048
	s_add_u32 s52, s52, s56
	s_addc_u32 s53, s53, s57
	s_add_u32 s54, s54, s56
	s_addc_u32 s55, s55, s57
	s_and_saveexec_b64 s[16:17], s[0:1]
	s_nop 6
	v_cvt_pk_bf16_f32 v46, v22, v23
	v_cvt_pk_bf16_f32 v47, v24, v25
	ds_write_b64 v172, v[46:47] offset:34880
	s_or_b64 exec, exec, s[16:17]
	s_waitcnt vmcnt(36)
	ds_bpermute_b32 v228, v109, v207
	s_waitcnt lgkmcnt(0)
	s_barrier
	s_and_b64 vcc, exec, s[4:5]
	s_cbranch_vccnz .LBB0_469
	v_cvt_pk_bf16_f32 v46, v148, s0
	ds_write_b16 v72, v46 offset:4608

.LBB0_473:
	s_cmp_gt_u32 s28, 62
	s_cbranch_scc1 .LBB0_479
	s_and_b64 vcc, exec, s[6:7]
	s_xor_b32 s6, s18, 0xffffff80
	s_cbranch_vccnz .LBB0_476
	global_load_dword v2, v97, s[36:37] nt
	global_load_dword v10, v50, s[38:39]
	global_load_dword v3, v98, s[36:37] nt
	global_load_dword v11, v51, s[38:39]
	global_load_dword v4, v99, s[36:37] nt
	global_load_dword v12, v52, s[38:39]
	global_load_dword v5, v100, s[36:37] nt
	global_load_dword v13, v53, s[38:39]
	global_load_dword v6, v101, s[36:37] nt
	global_load_dword v14, v54, s[38:39]
	global_load_dword v7, v102, s[36:37] nt
	global_load_dword v15, v55, s[38:39]
	global_load_dword v8, v103, s[36:37] nt
	global_load_dword v16, v56, s[38:39]
	global_load_dword v9, v104, s[36:37] nt
	global_load_dword v17, v57, s[38:39]
.LBB0_476:
	s_add_i32 s7, s25, -1
	s_and_b64 s[14:15], s[2:3], exec
	s_cselect_b32 s7, s19, s7
	s_lshl_b32 s14, s7, 14
	s_mov_b32 s15, s22
	v_lshl_add_u64 v[18:19], v[66:67], 0, s[14:15]
	global_load_dwordx4 v[18:21], v[18:19], off
	s_and_b64 vcc, exec, s[4:5]
	s_cbranch_vccnz .LBB0_478
	global_load_dword v148, v73, s[38:39]
.LBB0_478:
	global_load_dword v48, v73, s[38:39] offset:32
	s_add_u32 s36, s36, s40
	s_addc_u32 s37, s37, s57
	s_add_u32 s38, s38, s41
	s_addc_u32 s39, s39, s57
	s_branch .LBB0_480

.LBB0_480:
	ds_read_b128 v[208:211], v187
	v_add_u32_e32 v46, v87, v167
	ds_read_b128 v[212:215], v46
	ds_read_b128 v[230:233], v187 offset:64
	ds_read_b128 v[234:237], v46 offset:64
	ds_read_b128 v[238:241], v88
	ds_read_b128 v[242:245], v88 offset:64
	s_waitcnt lgkmcnt(4)
	v_mfma_f32_16x16x32_bf16 v[212:215], v[208:211], v[212:215], 0
	global_load_dword v151, v89, s[52:53]
	s_waitcnt lgkmcnt(1)
	v_mfma_f32_16x16x32_bf16 v[208:211], v[208:211], v[238:241], 0
	global_load_dword v152, v89, s[52:53] offset:2048
	v_mfma_f32_16x16x32_bf16 v[212:215], v[230:233], v[234:237], v[212:215]
	global_load_dword v153, v89, s[54:55]
	s_waitcnt lgkmcnt(0)
	v_mfma_f32_16x16x32_bf16 v[208:211], v[230:233], v[242:245], v[208:211]
	global_load_dword v154, v89, s[54:55] offset:2048
	ds_read_b128 v[230:233], v187 offset:128
	ds_read_b128 v[234:237], v46 offset:128
	ds_read_b128 v[238:241], v46 offset:192
	ds_read_b128 v[242:245], v187 offset:192
	s_waitcnt lgkmcnt(2)
	v_mfma_f32_16x16x32_bf16 v[212:215], v[230:233], v[234:237], v[212:215]
	global_load_dword v157, v90, s[52:53]
	ds_read_b128 v[234:237], v88 offset:128
	ds_read_b128 v[246:249], v88 offset:192
	s_waitcnt lgkmcnt(1)
	v_mfma_f32_16x16x32_bf16 v[208:211], v[230:233], v[234:237], v[208:211]
	global_load_dword v158, v90, s[52:53] offset:2048
	v_mfma_f32_16x16x32_bf16 v[212:215], v[242:245], v[238:241], v[212:215]
	global_load_dword v159, v90, s[54:55]
	s_waitcnt lgkmcnt(0)
	v_mfma_f32_16x16x32_bf16 v[208:211], v[242:245], v[246:249], v[208:211]
	global_load_dword v160, v90, s[54:55] offset:2048
	ds_read_b128 v[230:233], v187 offset:256
	ds_read_b128 v[234:237], v46 offset:256
	ds_read_b128 v[238:241], v46 offset:320
	ds_read_b128 v[242:245], v187 offset:320
	s_waitcnt lgkmcnt(2)
	v_mfma_f32_16x16x32_bf16 v[212:215], v[230:233], v[234:237], v[212:215]
	global_load_dword v161, v91, s[52:53]
	ds_read_b128 v[234:237], v88 offset:256
	ds_read_b128 v[246:249], v88 offset:320
	s_waitcnt lgkmcnt(1)
	v_mfma_f32_16x16x32_bf16 v[208:211], v[230:233], v[234:237], v[208:211]
	global_load_dword v162, v91, s[52:53] offset:2048
	v_mfma_f32_16x16x32_bf16 v[212:215], v[242:245], v[238:241], v[212:215]
	global_load_dword v164, v91, s[54:55]
	s_waitcnt lgkmcnt(0)
	v_mfma_f32_16x16x32_bf16 v[208:211], v[242:245], v[246:249], v[208:211]
	global_load_dword v165, v91, s[54:55] offset:2048
	ds_read_b128 v[230:233], v187 offset:384
	ds_read_b128 v[234:237], v46 offset:384
	ds_read_b128 v[238:241], v46 offset:448
	ds_read_b128 v[242:245], v187 offset:448
	s_waitcnt lgkmcnt(2)
	v_mfma_f32_16x16x32_bf16 v[212:215], v[230:233], v[234:237], v[212:215]
	global_load_dword v169, v92, s[52:53]
	ds_read_b128 v[234:237], v88 offset:384
	ds_read_b128 v[246:249], v88 offset:448
	s_waitcnt lgkmcnt(1)
	v_mfma_f32_16x16x32_bf16 v[208:211], v[230:233], v[234:237], v[208:211]
	global_load_dword v171, v92, s[52:53] offset:2048
	v_mfma_f32_16x16x32_bf16 v[212:215], v[242:245], v[238:241], v[212:215]
	global_load_dword v180, v92, s[54:55]
	s_waitcnt lgkmcnt(0)
	v_mfma_f32_16x16x32_bf16 v[208:211], v[242:245], v[246:249], v[208:211]
	global_load_dword v181, v92, s[54:55] offset:2048
	ds_bpermute_b32 v46, v176, v207
	ds_bpermute_b32 v47, v177, v207
	ds_bpermute_b32 v216, v178, v207
	ds_bpermute_b32 v207, v179, v207
	ds_read_b128 v[230:233], v188
	ds_read_b128 v[234:237], v218
	s_waitcnt lgkmcnt(5)
	v_mul_f32_e32 v46, 0x3fb8aa3b, v46
	s_waitcnt lgkmcnt(4)
	v_mul_f32_e32 v47, 0x3fb8aa3b, v47
	s_waitcnt lgkmcnt(3)
	v_mul_f32_e32 v216, 0x3fb8aa3b, v216
	s_waitcnt lgkmcnt(2)
	v_mul_f32_e32 v207, 0x3fb8aa3b, v207
	v_exp_f32_e32 v46, v46
	v_exp_f32_e32 v47, v47
	v_exp_f32_e32 v246, v216
	v_exp_f32_e32 v247, v207
	ds_read_b128 v[238:241], v206
	ds_read_b128 v[242:245], v188 offset:64
	v_pk_mul_f32 v[212:213], v[212:213], v[46:47]
	v_pk_mul_f32 v[208:209], v[208:209], v[46:47]
	v_pk_mul_f32 v[214:215], v[214:215], v[246:247]
	v_pk_mul_f32 v[210:211], v[210:211], v[246:247]
	v_add_u32_e32 v47, 64, v217
	s_waitcnt lgkmcnt(2)
	v_mfma_f32_16x16x32_bf16 v[212:215], v[230:233], v[234:237], v[212:215]
	global_load_dword v190, v93, s[52:53]
	s_waitcnt lgkmcnt(1)
	v_mfma_f32_16x16x32_bf16 v[208:211], v[230:233], v[238:241], v[208:211]
	global_load_dword v191, v93, s[52:53] offset:2048
	ds_read_b128 v[230:233], v110
	ds_read_b128 v[234:237], v219
	s_waitcnt lgkmcnt(1)
	v_mfma_f32_16x16x32_bf16 v[208:211], v[242:245], v[230:233], v[208:211]
	global_load_dword v192, v93, s[54:55]
	s_waitcnt lgkmcnt(0)
	v_mfma_f32_16x16x32_bf16 v[212:215], v[242:245], v[234:237], v[212:215]
	global_load_dword v193, v93, s[54:55] offset:2048
	s_nop 5
	ds_bpermute_b32 v46, v170, v208
	s_waitcnt lgkmcnt(0)
	v_max_f32_e64 v46, |v46|, |v46|
	v_max_f32_e32 v207, 1.0, v46
	v_div_scale_f32 v208, s[4:5], v207, v207, v212
	v_rcp_f32_e32 v216, v208
	v_subrev_u32_e32 v46, 64, v222
	v_cndmask_b32_e64 v46, v46, v47, s[2:3]
	v_ashrrev_i32_e32 v47, 31, v46
	v_fma_f32 v218, -v208, v216, 1.0
	v_fmac_f32_e32 v216, v218, v216
	v_div_scale_f32 v218, vcc, v212, v207, v212
	v_mul_f32_e32 v219, v218, v216
	v_fma_f32 v229, -v208, v219, v218
	v_fmac_f32_e32 v219, v229, v216
	v_fma_f32 v208, -v208, v219, v218
	v_div_fmas_f32 v208, v208, v216, v219
	v_div_fixup_f32 v207, v208, v207, v212
	ds_bpermute_b32 v208, v170, v209
	v_lshlrev_b64 v[46:47], 12, v[46:47]
	v_cvt_pk_bf16_f32 v207, v207, s0
	v_lshl_add_u64 v[46:47], v[70:71], 0, v[46:47]
	global_store_short v[46:47], v207, off offset:2048
	s_waitcnt lgkmcnt(0)
	v_max_f32_e64 v47, |v208|, |v208|
	v_max_f32_e32 v207, 1.0, v47
	v_div_scale_f32 v208, s[4:5], v207, v207, v213
	v_rcp_f32_e32 v209, v208
	v_add_u32_e32 v46, 0xffffffbf, v222
	v_add_u32_e32 v47, 0x41, v217
	v_cndmask_b32_e64 v46, v46, v47, s[2:3]
	v_fma_f32 v212, -v208, v209, 1.0
	v_fmac_f32_e32 v209, v212, v209
	v_div_scale_f32 v212, vcc, v213, v207, v213
	v_mul_f32_e32 v216, v212, v209
	v_fma_f32 v218, -v208, v216, v212
	v_fmac_f32_e32 v216, v218, v209
	v_fma_f32 v208, -v208, v216, v212
	v_div_fmas_f32 v208, v208, v209, v216
	v_div_fixup_f32 v207, v208, v207, v213
	ds_bpermute_b32 v208, v170, v210
	v_ashrrev_i32_e32 v47, 31, v46
	v_lshlrev_b64 v[46:47], 12, v[46:47]
	v_cvt_pk_bf16_f32 v207, v207, s0
	v_lshl_add_u64 v[46:47], v[70:71], 0, v[46:47]
	global_store_short v[46:47], v207, off offset:2048
	s_waitcnt lgkmcnt(0)
	v_max_f32_e64 v47, |v208|, |v208|
	v_max_f32_e32 v207, 1.0, v47
	v_div_scale_f32 v208, s[4:5], v207, v207, v214
	v_rcp_f32_e32 v209, v208
	v_add_u32_e32 v46, 0xfbd, v223
	v_add_u32_e32 v47, 0x42, v217
	v_cndmask_b32_e64 v46, v46, v47, s[2:3]
	v_fma_f32 v210, -v208, v209, 1.0
	v_fmac_f32_e32 v209, v210, v209
	v_div_scale_f32 v210, vcc, v214, v207, v214
	v_mul_f32_e32 v212, v210, v209
	v_fma_f32 v213, -v208, v212, v210
	v_fmac_f32_e32 v212, v213, v209
	v_fma_f32 v208, -v208, v212, v210
	v_div_fmas_f32 v208, v208, v209, v212
	v_div_fixup_f32 v207, v208, v207, v214
	ds_bpermute_b32 v208, v170, v211
	v_ashrrev_i32_e32 v47, 31, v46
	v_lshlrev_b64 v[46:47], 12, v[46:47]
	v_cvt_pk_bf16_f32 v207, v207, s0
	v_lshl_add_u64 v[46:47], v[70:71], 0, v[46:47]
	global_store_short v[46:47], v207, off offset:2048
	s_waitcnt lgkmcnt(0)
	v_max_f32_e64 v46, |v208|, |v208|
	ds_read_b128 v[208:211], v224 offset:33792
	v_max_f32_e32 v212, 1.0, v46
	v_mul_f32_e32 v46, 0x3fb8aa3b, v228
	v_exp_f32_e32 v46, v46
	v_add_u32_e32 v207, 0x43, v217
	ds_read_b128 v[216:219], v111
	ds_read_b128 v[228:231], v49 offset:33792
	v_add_u32_e32 v47, 0xfbc, v223
	v_pk_mul_f32 v[44:45], v[44:45], v[46:47] op_sel_hi:[1,0]
	v_pk_mul_f32 v[42:43], v[42:43], v[46:47] op_sel_hi:[1,0]
	ds_read_b128 v[232:235], v225
	v_div_scale_f32 v213, s[4:5], v212, v212, v215
	s_waitcnt lgkmcnt(2)
	v_mfma_f32_16x16x32_bf16 v[42:45], v[208:211], v[216:219], v[42:45]
	global_load_dword v194, v94, s[52:53]
	v_rcp_f32_e32 v214, v213
	v_cndmask_b32_e64 v222, v47, v207, s[2:3]
	v_ashrrev_i32_e32 v223, 31, v222
	s_waitcnt lgkmcnt(0)
	v_mfma_f32_16x16x32_bf16 v[42:45], v[228:231], v[232:235], v[42:45]
	global_load_dword v195, v94, s[52:53] offset:2048
	v_fma_f32 v47, -v213, v214, 1.0
	v_fmac_f32_e32 v214, v47, v214
	v_div_scale_f32 v47, vcc, v215, v212, v215
	v_pk_mul_f32 v[40:41], v[40:41], v[46:47] op_sel_hi:[1,0]
	s_nop 3
	v_cvt_pk_bf16_f32 v208, v42, v43
	v_cvt_pk_bf16_f32 v209, v44, v45
	ds_write_b64 v189, v[208:209]
	ds_read_b128 v[208:211], v49 offset:33792
	ds_read_b128 v[216:219], v224 offset:33792
	ds_read_b128 v[228:231], v226
	ds_read_b128 v[232:235], v227
	v_pk_mul_f32 v[38:39], v[38:39], v[46:47] op_sel_hi:[1,0]
	v_mul_f32_e32 v207, v47, v214
	s_waitcnt lgkmcnt(1)
	v_mfma_f32_16x16x32_bf16 v[38:41], v[216:219], v[228:231], v[38:41]
	global_load_dword v196, v94, s[54:55]
	v_fma_f32 v216, -v213, v207, v47
	v_fmac_f32_e32 v207, v216, v214
	v_fma_f32 v47, -v213, v207, v47
	s_waitcnt lgkmcnt(0)
	v_mfma_f32_16x16x32_bf16 v[38:41], v[208:211], v[232:235], v[38:41]
	global_load_dword v197, v94, s[54:55] offset:2048
	v_div_fmas_f32 v47, v47, v214, v207
	v_div_fixup_f32 v47, v47, v212, v215
	v_cvt_pk_bf16_f32 v47, v47, s0
	v_pk_mul_f32 v[36:37], v[36:37], v[46:47] op_sel_hi:[1,0]
	v_pk_mul_f32 v[34:35], v[34:35], v[46:47] op_sel_hi:[1,0]
	s_nop 2
	v_cvt_pk_bf16_f32 v208, v38, v39
	v_cvt_pk_bf16_f32 v209, v40, v41
	ds_write_b64 v189, v[208:209] offset:8448
	ds_read_b128 v[208:211], v49 offset:33792
	ds_read_b128 v[216:219], v224 offset:33792
	ds_read_b128 v[212:215], v206
	ds_read_b128 v[228:231], v110
	s_waitcnt lgkmcnt(1)
	v_mfma_f32_16x16x32_bf16 v[34:37], v[216:219], v[212:215], v[34:37]
	global_load_dword v198, v95, s[52:53]
	v_lshlrev_b64 v[212:213], 12, v[222:223]
	v_lshl_add_u64 v[212:213], v[70:71], 0, v[212:213]
	global_store_short v[212:213], v47, off offset:2048
	s_waitcnt lgkmcnt(0)
	v_mfma_f32_16x16x32_bf16 v[34:37], v[208:211], v[228:231], v[34:37]
	global_load_dword v199, v95, s[52:53] offset:2048
	s_and_saveexec_b64 s[4:5], s[0:1]
	s_nop 6
	v_cvt_pk_bf16_f32 v208, v34, v35
	v_cvt_pk_bf16_f32 v209, v36, v37
	ds_write_b64 v172, v[208:209] offset:16896
	s_or_b64 exec, exec, s[4:5]
	ds_read_b128 v[208:211], v224 offset:36096
	ds_read_b128 v[212:215], v111
	ds_read_b128 v[216:219], v49 offset:36096
	v_mov_b32_e32 v47, v46
	v_mov_b32_e32 v222, v46
	v_mov_b32_e32 v223, v46
	v_pk_mul_f32 v[28:29], v[28:29], v[222:223]
	v_pk_mul_f32 v[26:27], v[26:27], v[46:47]
	v_pk_mul_f32 v[32:33], v[32:33], v[222:223]
	v_pk_mul_f32 v[30:31], v[30:31], v[46:47]
	s_waitcnt lgkmcnt(1)
	v_mfma_f32_16x16x32_bf16 v[26:29], v[208:211], v[212:215], v[26:29]
	global_load_dword v200, v95, s[54:55]
	ds_read_b128 v[208:211], v225
	v_pk_mul_f32 v[24:25], v[24:25], v[222:223]
	v_pk_mul_f32 v[22:23], v[22:23], v[46:47]
	s_waitcnt lgkmcnt(0)
	v_mfma_f32_16x16x32_bf16 v[26:29], v[216:219], v[208:211], v[26:29]
	global_load_dword v201, v95, s[54:55] offset:2048
	s_nop 7
	v_cvt_pk_bf16_f32 v208, v26, v27
	v_cvt_pk_bf16_f32 v209, v28, v29
	ds_write_b64 v189, v[208:209] offset:32
	ds_read_b128 v[208:211], v224 offset:36096
	ds_read_b128 v[212:215], v226
	ds_read_b128 v[216:219], v49 offset:36096
	ds_read_b128 v[226:229], v227
	s_waitcnt lgkmcnt(2)
	v_mfma_f32_16x16x32_bf16 v[30:33], v[208:211], v[212:215], v[30:33]
	global_load_dword v202, v96, s[52:53]
	s_waitcnt lgkmcnt(0)
	v_mfma_f32_16x16x32_bf16 v[30:33], v[216:219], v[226:229], v[30:33]
	global_load_dword v203, v96, s[52:53] offset:2048
	s_nop 7
	v_cvt_pk_bf16_f32 v208, v30, v31
	v_cvt_pk_bf16_f32 v209, v32, v33
	ds_write_b64 v189, v[208:209] offset:8480
	ds_read_b128 v[208:211], v224 offset:36096
	ds_read_b128 v[212:215], v206
	ds_read_b128 v[216:219], v49 offset:36096
	ds_read_b128 v[222:225], v110
	s_waitcnt lgkmcnt(2)
	v_mfma_f32_16x16x32_bf16 v[22:25], v[208:211], v[212:215], v[22:25]
	global_load_dword v204, v96, s[54:55]
	s_waitcnt lgkmcnt(0)
	v_mfma_f32_16x16x32_bf16 v[22:25], v[216:219], v[222:225], v[22:25]
	global_load_dword v205, v96, s[54:55] offset:2048
	s_add_u32 s52, s52, s56
	s_addc_u32 s53, s53, s57
	s_add_u32 s54, s54, s56
	s_addc_u32 s55, s55, s57
	s_and_saveexec_b64 s[4:5], s[0:1]
	s_cbranch_execz .LBB0_452
	s_nop 5
	v_cvt_pk_bf16_f32 v46, v22, v23
	v_cvt_pk_bf16_f32 v47, v24, v25
	ds_write_b64 v172, v[46:47] offset:16928
	s_branch .LBB0_452
.LBB0_484:
	s_waitcnt vmcnt(0)
	s_mov_b64 s[2:3], 0

.LBB0_654:
	s_sleep 1
	global_load_dword v3, v2, s[12:13] sc1
	s_waitcnt vmcnt(0)
	v_cmp_gt_u32_e32 vcc, 8, v3
	s_cbranch_vccnz .LBB0_654
.LBB0_655:
	s_waitcnt vmcnt(0)
.LBB0_656:
	s_or_b64 exec, exec, s[2:3]
	s_waitcnt vmcnt(0) lgkmcnt(0)
	s_barrier
	s_and_saveexec_b64 s[2:3], s[0:1]
	s_cbranch_execz .LBB0_658
	s_lshl_b32 s0, s6, 3
	s_ashr_i32 s1, s0, 31
	s_waitcnt lgkmcnt(0)
	v_lshl_add_u64 v[2:3], v[0:1], 3, s[10:11]
	s_lshl_b64 s[6:7], s[0:1], 11
	v_lshl_add_u64 v[4:5], v[2:3], 0, s[6:7]
	s_or_b32 s6, s0, 1
	s_ashr_i32 s7, s6, 31
	s_lshl_b64 s[6:7], s[6:7], 11
	v_lshl_add_u64 v[6:7], v[2:3], 0, s[6:7]
	s_or_b32 s6, s0, 2
	s_ashr_i32 s7, s6, 31
	s_lshl_b64 s[6:7], s[6:7], 11
	v_lshl_add_u64 v[8:9], v[2:3], 0, s[6:7]
	s_or_b32 s6, s0, 3
	s_ashr_i32 s7, s6, 31
	s_lshl_b64 s[6:7], s[6:7], 11
	v_lshl_add_u64 v[10:11], v[2:3], 0, s[6:7]
	s_or_b32 s6, s0, 4
	s_ashr_i32 s7, s6, 31
	s_lshl_b64 s[6:7], s[6:7], 11
	v_lshl_add_u64 v[12:13], v[2:3], 0, s[6:7]
	s_or_b32 s6, s0, 5
	global_load_dwordx2 v[4:5], v[4:5], off sc1
	s_ashr_i32 s7, s6, 31
	global_load_dwordx2 v[6:7], v[6:7], off sc1
	s_lshl_b64 s[6:7], s[6:7], 11
	global_load_dwordx2 v[8:9], v[8:9], off sc1
	v_lshl_add_u64 v[14:15], v[2:3], 0, s[6:7]
	s_or_b32 s6, s0, 6
	global_load_dwordx2 v[10:11], v[10:11], off sc1
	s_ashr_i32 s7, s6, 31
	s_or_b32 s0, s0, 7
	global_load_dwordx2 v[12:13], v[12:13], off sc1
	s_lshl_b64 s[6:7], s[6:7], 11
	s_ashr_i32 s1, s0, 31
	global_load_dwordx2 v[14:15], v[14:15], off sc1
	v_lshl_add_u64 v[16:17], v[2:3], 0, s[6:7]
	s_lshl_b64 s[0:1], s[0:1], 11
	global_load_dwordx2 v[16:17], v[16:17], off sc1
	v_lshl_add_u64 v[2:3], v[2:3], 0, s[0:1]
	global_load_dwordx2 v[2:3], v[2:3], off sc1
	s_mov_b32 s0, 0x3a000000
	s_mov_b32 s1, 0xf800000
	v_lshl_add_u32 v0, v0, 3, 0
	s_waitcnt vmcnt(7)
	v_add_f32_e32 v1, 0, v4
	v_add_f32_e32 v4, 0, v5
	s_waitcnt vmcnt(6)
	v_add_f32_e32 v1, v1, v6
	v_add_f32_e32 v4, v4, v7
	s_waitcnt vmcnt(5)
	v_add_f32_e32 v1, v1, v8
	v_add_f32_e32 v4, v4, v9
	s_waitcnt vmcnt(4)
	v_add_f32_e32 v1, v1, v10
	v_add_f32_e32 v4, v4, v11
	s_waitcnt vmcnt(3)
	v_add_f32_e32 v1, v1, v12
	v_add_f32_e32 v4, v4, v13
	s_waitcnt vmcnt(2)
	v_add_f32_e32 v1, v1, v14
	v_add_f32_e32 v4, v4, v15
	s_waitcnt vmcnt(1)
	v_add_f32_e32 v1, v1, v16
	v_add_f32_e32 v4, v4, v17
	s_waitcnt vmcnt(0)
	v_add_f32_e32 v1, v1, v2
	v_mul_f32_e32 v2, 0x3a000000, v1
	v_add_f32_e32 v3, v4, v3
	v_mul_f32_e32 v1, v2, v2
	v_fma_f32 v1, v3, s0, -v1
	v_max_f32_e32 v1, 0, v1
	v_add_f32_e32 v1, 0x3727c5ac, v1
	v_mul_f32_e32 v3, 0x4f800000, v1
	v_cmp_gt_f32_e32 vcc, s1, v1
	v_mov_b32_e32 v4, 0x260
	s_nop 0
	v_cndmask_b32_e32 v1, v1, v3, vcc
	v_sqrt_f32_e32 v3, v1
	s_nop 0
	v_add_u32_e32 v5, -1, v3
	v_add_u32_e32 v6, 1, v3
	v_fma_f32 v7, -v5, v3, v1
	v_fma_f32 v8, -v6, v3, v1
	v_cmp_ge_f32_e64 s[0:1], 0, v7
	s_nop 1
	v_cndmask_b32_e64 v3, v3, v5, s[0:1]
	v_cmp_lt_f32_e64 s[0:1], 0, v8
	s_nop 1
	v_cndmask_b32_e64 v3, v3, v6, s[0:1]
	v_mul_f32_e32 v5, 0x37800000, v3
	v_cndmask_b32_e32 v3, v3, v5, vcc
	v_cmp_class_f32_e32 vcc, v1, v4
	s_nop 1
	v_cndmask_b32_e32 v1, v3, v1, vcc
	v_div_scale_f32 v3, s[0:1], v1, v1, 1.0
	v_rcp_f32_e32 v4, v3
	v_div_scale_f32 v5, vcc, 1.0, v1, 1.0
	v_fma_f32 v6, -v3, v4, 1.0
	v_fmac_f32_e32 v4, v6, v4
	v_mul_f32_e32 v6, v5, v4
	v_fma_f32 v7, -v3, v6, v5
	v_fmac_f32_e32 v6, v7, v4
	v_fma_f32 v3, -v3, v6, v5
	v_div_fmas_f32 v3, v3, v4, v6
	v_div_fixup_f32 v3, v3, v1, 1.0
	ds_write_b64 v0, v[2:3] offset:8192

.LBB0_827:
	s_sleep 1
	global_load_dword v3, v2, s[12:13] sc1
	s_waitcnt vmcnt(0)
	v_cmp_gt_u32_e32 vcc, 8, v3
	s_cbranch_vccnz .LBB0_827
.LBB0_828:
	s_waitcnt vmcnt(0)
.LBB0_829:
	s_or_b64 exec, exec, s[4:5]
	s_waitcnt vmcnt(0) lgkmcnt(0)
	s_barrier
	s_and_saveexec_b64 s[4:5], s[2:3]
	s_cbranch_execz .LBB0_831
	s_lshl_b32 s2, s26, 3
	s_ashr_i32 s3, s2, 31
	s_waitcnt lgkmcnt(0)
	v_lshl_add_u64 v[2:3], v[0:1], 3, s[6:7]
	s_lshl_b64 s[6:7], s[2:3], 11
	v_lshl_add_u64 v[4:5], v[2:3], 0, s[6:7]
	s_or_b32 s6, s2, 1
	s_ashr_i32 s7, s6, 31
	s_lshl_b64 s[6:7], s[6:7], 11
	v_lshl_add_u64 v[6:7], v[2:3], 0, s[6:7]
	s_or_b32 s6, s2, 2
	s_ashr_i32 s7, s6, 31
	s_lshl_b64 s[6:7], s[6:7], 11
	v_lshl_add_u64 v[8:9], v[2:3], 0, s[6:7]
	s_or_b32 s6, s2, 3
	s_ashr_i32 s7, s6, 31
	s_lshl_b64 s[6:7], s[6:7], 11
	v_lshl_add_u64 v[10:11], v[2:3], 0, s[6:7]
	s_or_b32 s6, s2, 4
	s_ashr_i32 s7, s6, 31
	s_lshl_b64 s[6:7], s[6:7], 11
	v_lshl_add_u64 v[12:13], v[2:3], 0, s[6:7]
	s_or_b32 s6, s2, 5
	global_load_dwordx2 v[4:5], v[4:5], off sc1
	s_ashr_i32 s7, s6, 31
	global_load_dwordx2 v[6:7], v[6:7], off sc1
	s_lshl_b64 s[6:7], s[6:7], 11
	global_load_dwordx2 v[8:9], v[8:9], off sc1
	v_lshl_add_u64 v[14:15], v[2:3], 0, s[6:7]
	s_or_b32 s6, s2, 6
	global_load_dwordx2 v[10:11], v[10:11], off sc1
	s_ashr_i32 s7, s6, 31
	s_or_b32 s2, s2, 7
	global_load_dwordx2 v[12:13], v[12:13], off sc1
	s_lshl_b64 s[6:7], s[6:7], 11
	s_ashr_i32 s3, s2, 31
	global_load_dwordx2 v[14:15], v[14:15], off sc1
	v_lshl_add_u64 v[16:17], v[2:3], 0, s[6:7]
	s_lshl_b64 s[2:3], s[2:3], 11
	global_load_dwordx2 v[16:17], v[16:17], off sc1
	v_lshl_add_u64 v[2:3], v[2:3], 0, s[2:3]
	global_load_dwordx2 v[2:3], v[2:3], off sc1
	s_mov_b32 s2, 0x3a000000
	s_mov_b32 s3, 0xf800000
	v_lshl_add_u32 v0, v0, 3, 0
	s_waitcnt vmcnt(7)
	v_add_f32_e32 v1, 0, v4
	v_add_f32_e32 v4, 0, v5
	s_waitcnt vmcnt(6)
	v_add_f32_e32 v1, v1, v6
	v_add_f32_e32 v4, v4, v7
	s_waitcnt vmcnt(5)
	v_add_f32_e32 v1, v1, v8
	v_add_f32_e32 v4, v4, v9
	s_waitcnt vmcnt(4)
	v_add_f32_e32 v1, v1, v10
	v_add_f32_e32 v4, v4, v11
	s_waitcnt vmcnt(3)
	v_add_f32_e32 v1, v1, v12
	v_add_f32_e32 v4, v4, v13
	s_waitcnt vmcnt(2)
	v_add_f32_e32 v1, v1, v14
	v_add_f32_e32 v4, v4, v15
	s_waitcnt vmcnt(1)
	v_add_f32_e32 v1, v1, v16
	v_add_f32_e32 v4, v4, v17
	s_waitcnt vmcnt(0)
	v_add_f32_e32 v1, v1, v2
	v_mul_f32_e32 v2, 0x3a000000, v1
	v_add_f32_e32 v3, v4, v3
	v_mul_f32_e32 v1, v2, v2
	v_fma_f32 v1, v3, s2, -v1
	v_max_f32_e32 v1, 0, v1
	v_add_f32_e32 v1, 0x3727c5ac, v1
	v_mul_f32_e32 v3, 0x4f800000, v1
	v_cmp_gt_f32_e32 vcc, s3, v1
	v_mov_b32_e32 v4, 0x260
	s_nop 0
	v_cndmask_b32_e32 v1, v1, v3, vcc
	v_sqrt_f32_e32 v3, v1
	s_nop 0
	v_add_u32_e32 v5, -1, v3
	v_add_u32_e32 v6, 1, v3
	v_fma_f32 v7, -v5, v3, v1
	v_fma_f32 v8, -v6, v3, v1
	v_cmp_ge_f32_e64 s[2:3], 0, v7
	s_nop 1
	v_cndmask_b32_e64 v3, v3, v5, s[2:3]
	v_cmp_lt_f32_e64 s[2:3], 0, v8
	s_nop 1
	v_cndmask_b32_e64 v3, v3, v6, s[2:3]
	v_mul_f32_e32 v5, 0x37800000, v3
	v_cndmask_b32_e32 v3, v3, v5, vcc
	v_cmp_class_f32_e32 vcc, v1, v4
	s_nop 1
	v_cndmask_b32_e32 v1, v3, v1, vcc
	v_div_scale_f32 v3, s[2:3], v1, v1, 1.0
	v_rcp_f32_e32 v4, v3
	v_div_scale_f32 v5, vcc, 1.0, v1, 1.0
	v_fma_f32 v6, -v3, v4, 1.0
	v_fmac_f32_e32 v4, v6, v4
	v_mul_f32_e32 v6, v5, v4
	v_fma_f32 v7, -v3, v6, v5
	v_fmac_f32_e32 v6, v7, v4
	v_fma_f32 v3, -v3, v6, v5
	v_div_fmas_f32 v3, v3, v4, v6
	v_div_fixup_f32 v3, v3, v1, 1.0
	ds_write_b64 v0, v[2:3] offset:8192
